# GLA pass 0/1: packed f32 mul/add beside the MFMAs split into scalar pairs (bit-identical)
# speedup vs baseline: 1.0061x; 1.0042x over previous
.LBB0_585:
	s_or_b64 exec, exec, s[6:7]
	s_waitcnt lgkmcnt(0)
	ds_read2st64_b32 v[46:47], v46 offset0:35 offset1:39
	v_add_f32_e32 v18, v18, v36
	v_add_f32_e32 v19, v19, v18
	v_add_f32_e32 v24, v24, v19
	v_add_f32_e32 v25, v25, v24
	s_waitcnt lgkmcnt(0)
	v_add_f32_e32 v46, v64, v46
	v_cndmask_b32_e64 v64, v46, v64, s[4:5]
	v_add_f32_e32 v53, v53, v64
	v_add_f32_e32 v52, v52, v53
	v_add_f32_e32 v51, v51, v52
	v_add_f32_e32 v50, v50, v51
	v_add_f32_e32 v49, v49, v50
	v_add_f32_e32 v48, v48, v49
	v_add_f32_e32 v45, v45, v48
	v_add_f32_e32 v44, v44, v45
	v_add_f32_e32 v43, v43, v44
	v_add_f32_e32 v42, v42, v43
	v_add_f32_e32 v41, v41, v42
	v_add_f32_e32 v40, v40, v41
	v_add_f32_e32 v39, v39, v40
	v_add_f32_e32 v20, v20, v25
	v_add_f32_e32 v38, v38, v39
	v_add_f32_e32 v21, v21, v20
	v_and_b32_e32 v65, 0xfffff3f, v54
	v_add_f32_e32 v37, v37, v38
	v_add_f32_e32 v16, v16, v21
	v_mul_lo_u32 v108, v65, s28
	v_exp_f32_e32 v65, v64
	v_exp_f32_e32 v64, v53
	v_exp_f32_e32 v53, v52
	v_exp_f32_e32 v52, v51
	v_exp_f32_e32 v51, v50
	v_exp_f32_e32 v50, v49
	v_exp_f32_e32 v49, v48
	v_exp_f32_e32 v48, v45
	v_exp_f32_e32 v45, v44
	v_exp_f32_e32 v44, v43
	v_exp_f32_e32 v43, v42
	v_exp_f32_e32 v42, v41
	v_exp_f32_e32 v41, v40
	v_exp_f32_e32 v40, v39
	v_exp_f32_e32 v39, v38
	v_exp_f32_e32 v38, v37
	v_add_f32_e32 v17, v17, v16
	v_add_f32_e32 v22, v22, v17
	v_add_f32_e32 v23, v23, v22
	v_lshlrev_b32_e32 v75, 16, v117
	v_lshlrev_b32_e32 v74, 16, v116
	v_lshlrev_b32_e32 v77, 16, v115
	v_lshlrev_b32_e32 v76, 16, v114
	v_lshlrev_b32_e32 v79, 16, v113
	v_lshlrev_b32_e32 v78, 16, v112
	v_lshlrev_b32_e32 v131, 16, v111
	v_lshlrev_b32_e32 v130, 16, v110
	v_add_f32_e32 v30, v30, v23
	v_lshlrev_b32_e32 v63, 5, v63
	v_lshlrev_b32_e32 v67, 16, v125
	v_lshlrev_b32_e32 v66, 16, v124
	v_lshlrev_b32_e32 v69, 16, v123
	v_lshlrev_b32_e32 v68, 16, v122
	v_lshlrev_b32_e32 v71, 16, v121
	v_lshlrev_b32_e32 v70, 16, v120
	v_lshlrev_b32_e32 v73, 16, v119
	v_lshlrev_b32_e32 v72, 16, v118
	v_mul_f32_e32 v44, v44, v74
	v_mul_f32_e32 v45, v45, v75
	v_mul_f32_e32 v42, v42, v76
	v_mul_f32_e32 v43, v43, v77
	v_mul_f32_e32 v40, v40, v78
	v_mul_f32_e32 v41, v41, v79
	v_mul_f32_e32 v38, v38, v130
	v_mul_f32_e32 v39, v39, v131
	v_add_f32_e32 v31, v31, v30
	v_mul_f32_e32 v64, v64, v66
	v_mul_f32_e32 v65, v65, v67
	v_mul_f32_e32 v52, v52, v68
	v_mul_f32_e32 v53, v53, v69
	v_mul_f32_e32 v50, v50, v70
	v_mul_f32_e32 v51, v51, v71
	v_mul_f32_e32 v48, v48, v72
	v_mul_f32_e32 v49, v49, v73
	v_add3_u32 v37, 0, v108, v63
	v_cvt_pk_bf16_f32 v38, v38, v39
	v_cvt_pk_bf16_f32 v39, v40, v41
	v_cvt_pk_bf16_f32 v40, v42, v43
	v_cvt_pk_bf16_f32 v41, v44, v45
	v_add_f32_e32 v28, v28, v31
	ds_write_b128 v37, v[38:41] offset:47104
	v_cvt_pk_bf16_f32 v38, v48, v49
	v_cvt_pk_bf16_f32 v39, v50, v51
	v_cvt_pk_bf16_f32 v40, v52, v53
	v_cvt_pk_bf16_f32 v41, v64, v65
	v_add_f32_e32 v29, v29, v28
	ds_write_b128 v37, v[38:41] offset:47120
	v_exp_f32_e32 v38, v36
	v_exp_f32_e32 v39, v18
	v_exp_f32_e32 v18, v19
	v_exp_f32_e32 v19, v24
	v_exp_f32_e32 v24, v25
	v_exp_f32_e32 v25, v20
	v_exp_f32_e32 v20, v21
	v_exp_f32_e32 v21, v16
	v_add_f32_e32 v26, v26, v29
	v_exp_f32_e32 v16, v17
	v_exp_f32_e32 v17, v22
	v_exp_f32_e32 v22, v23
	v_exp_f32_e32 v23, v30
	v_exp_f32_e32 v30, v31
	v_exp_f32_e32 v31, v28
	v_exp_f32_e32 v28, v29
	v_exp_f32_e32 v29, v26
	v_mul_f32_e32 v38, v38, v130
	v_mul_f32_e32 v39, v39, v131
	v_mul_f32_e32 v18, v18, v78
	v_mul_f32_e32 v19, v19, v79
	v_mul_f32_e32 v24, v24, v76
	v_mul_f32_e32 v25, v25, v77
	v_mul_f32_e32 v20, v20, v74
	v_mul_f32_e32 v21, v21, v75
	s_and_b32 s6, s21, 2
	v_mul_f32_e32 v40, v16, v72
	v_mul_f32_e32 v41, v17, v73
	v_mul_f32_e32 v22, v22, v70
	v_mul_f32_e32 v23, v23, v71
	v_mul_f32_e32 v30, v30, v68
	v_mul_f32_e32 v31, v31, v69
	v_mul_f32_e32 v28, v28, v66
	v_mul_f32_e32 v29, v29, v67
	v_cvt_pk_bf16_f32 v16, v38, v39
	v_cvt_pk_bf16_f32 v17, v18, v19
	v_cvt_pk_bf16_f32 v18, v24, v25
	v_cvt_pk_bf16_f32 v19, v20, v21
	s_ashr_i32 s16, s33, 1
	v_add_u32_e32 v36, s6, v33
	ds_write_b128 v37, v[16:19] offset:56320
	v_cvt_pk_bf16_f32 v16, v40, v41
	v_cvt_pk_bf16_f32 v17, v22, v23
	v_cvt_pk_bf16_f32 v18, v30, v31
	v_cvt_pk_bf16_f32 v19, v28, v29
	ds_write_b128 v37, v[16:19] offset:56336
	s_and_saveexec_b64 s[4:5], vcc
	s_cbranch_execz .LBB0_587
	v_add_f32_e32 v16, v35, v46
	s_lshl_b32 s6, s16, 3
	v_exp_f32_e32 v21, v16
	v_lshl_add_u32 v16, v36, 1, s6
	v_ashrrev_i32_e32 v17, 31, v16
	v_lshlrev_b64 v[18:19], 8, v[16:17]
	v_add_f32_e32 v20, v62, v47
	v_lshl_add_u64 v[18:19], s[14:15], 0, v[18:19]
	v_lshlrev_b32_e32 v108, 2, v128
	v_lshl_add_u64 v[18:19], v[18:19], 0, v[108:109]
	v_add_f32_e32 v17, v27, v20
	v_or_b32_e32 v16, 1, v16
	global_store_dword v[18:19], v21, off
	v_exp_f32_e32 v18, v17
	v_ashrrev_i32_e32 v17, 31, v16
	v_lshlrev_b64 v[16:17], 8, v[16:17]
	v_lshl_add_u64 v[16:17], s[14:15], 0, v[16:17]
	v_lshl_add_u64 v[16:17], v[16:17], 0, v[108:109]
	global_store_dword v[16:17], v18, off

.LBB0_700:
	s_or_b64 exec, exec, s[4:5]
	v_lshlrev_b32_e32 v49, 6, v195
	v_or_b32_e32 v50, v49, v194
	v_lshlrev_b32_e32 v97, 2, v50
	s_waitcnt lgkmcnt(0)
	s_barrier
	global_load_dwordx4 v[50:53], v97, s[18:19]
	global_load_dwordx4 v[54:57], v97, s[18:19] offset:32
	v_lshlrev_b32_e32 v96, 5, v193
	v_bitop3_b32 v96, v96, 32, v191 bitop3:0x36
	v_lshl_add_u32 v96, v96, 2, 0
	ds_read_b32 v96, v96 offset:8192
	v_lshlrev_b64 v[58:59], 11, v[166:167]
	v_lshl_add_u64 v[58:59], s[6:7], 0, v[58:59]
	v_lshlrev_b32_e32 v148, 4, v192
	v_lshl_add_u64 v[58:59], v[162:163], 1, v[58:59]
	s_waitcnt lgkmcnt(0)
	v_add_f32_e32 v48, v48, v96
	v_fmamk_f32 v48, v48, 0x3c000000, v173
	v_lshl_add_u64 v[58:59], v[58:59], 0, v[148:149]
	v_lshlrev_b32_e32 v148, 1, v49
	v_mul_f32_e32 v49, 0x4b800000, v48
	v_cmp_gt_f32_e32 vcc, s40, v48
	v_lshlrev_b32_e32 v60, 16, v168
	v_and_b32_e32 v61, 0xffff0000, v168
	v_cndmask_b32_e32 v48, v48, v49, vcc
	v_rsq_f32_e32 v96, v48
	v_lshlrev_b32_e32 v62, 16, v169
	v_and_b32_e32 v63, 0xffff0000, v169
	v_lshlrev_b32_e32 v92, 16, v164
	v_mul_f32_e32 v98, 0x45800000, v96
	v_cndmask_b32_e32 v96, v96, v98, vcc
	v_mul_f32_e32 v32, v32, v96
	v_mul_f32_e32 v33, v33, v96
	v_mul_f32_e32 v34, v34, v96
	v_mul_f32_e32 v35, v35, v96
	v_mul_f32_e32 v36, v36, v96
	v_mul_f32_e32 v37, v37, v96
	v_mul_f32_e32 v38, v38, v96
	v_mul_f32_e32 v39, v39, v96
	v_and_b32_e32 v93, 0xffff0000, v164
	v_lshlrev_b32_e32 v94, 16, v165
	v_and_b32_e32 v95, 0xffff0000, v165
	v_lshl_add_u64 v[58:59], v[58:59], 0, v[148:149]
	v_add_co_u32_e64 v48, s[4:5], s41, v58
	v_mul_f32_e32 v40, v40, v96
	v_mul_f32_e32 v41, v41, v96
	s_nop 0
	v_addc_co_u32_e64 v49, s[4:5], 0, v59, s[4:5]
	v_mul_f32_e32 v42, v42, v96
	v_mul_f32_e32 v43, v43, v96
	v_mul_f32_e32 v44, v44, v96
	v_mul_f32_e32 v45, v45, v96
	v_mul_f32_e32 v46, v46, v96
	v_mul_f32_e32 v47, v47, v96
	v_mul_f32_e32 v16, v16, v96
	v_mul_f32_e32 v17, v17, v96
	v_mul_f32_e32 v18, v18, v96
	v_mul_f32_e32 v19, v19, v96
	v_mul_f32_e32 v20, v20, v96
	v_mul_f32_e32 v21, v21, v96
	v_mul_f32_e32 v22, v22, v96
	v_mul_f32_e32 v23, v23, v96
	v_mul_f32_e32 v24, v24, v96
	v_mul_f32_e32 v25, v25, v96
	v_mul_f32_e32 v26, v26, v96
	v_mul_f32_e32 v27, v27, v96
	v_mul_f32_e32 v28, v28, v96
	v_mul_f32_e32 v29, v29, v96
	v_mul_f32_e32 v30, v30, v96
	v_mul_f32_e32 v31, v31, v96
	s_add_i32 s36, s36, s37
	s_andn2_b64 vcc, exec, s[26:27]
	s_mov_b32 s28, s42
	s_waitcnt vmcnt(1)
	v_mul_f32_e32 v32, v50, v32
	v_mul_f32_e32 v33, v51, v33
	v_mul_f32_e32 v34, v52, v34
	v_mul_f32_e32 v35, v53, v35
	s_waitcnt vmcnt(0)
	v_mul_f32_e32 v36, v54, v36
	v_mul_f32_e32 v37, v55, v37
	v_mul_f32_e32 v38, v56, v38
	v_mul_f32_e32 v39, v57, v39
	v_mul_f32_e32 v32, v32, v60
	v_mul_f32_e32 v33, v33, v61
	v_mul_f32_e32 v34, v34, v62
	v_mul_f32_e32 v35, v35, v63
	v_mul_f32_e32 v36, v36, v92
	v_mul_f32_e32 v37, v37, v93
	v_mul_f32_e32 v38, v38, v94
	v_mul_f32_e32 v39, v39, v95
	v_cvt_pk_bf16_f32 v32, v32, v33
	v_cvt_pk_bf16_f32 v33, v34, v35
	v_cvt_pk_bf16_f32 v34, v36, v37
	v_cvt_pk_bf16_f32 v35, v38, v39
	s_nop 0
	v_permlane32_swap_b32_e32 v32, v34
	v_permlane32_swap_b32_e32 v33, v35
	global_store_dwordx4 v[48:49], v[32:35], off offset:1024
	global_load_dwordx4 v[32:35], v97, s[18:19] offset:64
	s_nop 0
	global_load_dwordx4 v[36:39], v97, s[18:19] offset:96
	v_lshlrev_b32_e32 v48, 16, v160
	v_and_b32_e32 v49, 0xffff0000, v160
	v_lshlrev_b32_e32 v50, 16, v161
	v_and_b32_e32 v51, 0xffff0000, v161
	v_lshlrev_b32_e32 v52, 16, v158
	v_and_b32_e32 v53, 0xffff0000, v158
	v_lshlrev_b32_e32 v54, 16, v159
	v_and_b32_e32 v55, 0xffff0000, v159
	v_lshl_add_u64 v[56:57], v[58:59], 0, s[20:21]
	s_waitcnt vmcnt(1)
	v_mul_f32_e32 v32, v32, v40
	v_mul_f32_e32 v33, v33, v41
	v_mul_f32_e32 v34, v34, v42
	v_mul_f32_e32 v35, v35, v43
	s_waitcnt vmcnt(0)
	v_mul_f32_e32 v36, v36, v44
	v_mul_f32_e32 v37, v37, v45
	v_mul_f32_e32 v38, v38, v46
	v_mul_f32_e32 v39, v39, v47
	v_mul_f32_e32 v32, v32, v48
	v_mul_f32_e32 v33, v33, v49
	v_mul_f32_e32 v34, v34, v50
	v_mul_f32_e32 v35, v35, v51
	v_mul_f32_e32 v36, v36, v52
	v_mul_f32_e32 v37, v37, v53
	v_mul_f32_e32 v38, v38, v54
	v_mul_f32_e32 v39, v39, v55
	v_cvt_pk_bf16_f32 v32, v32, v33
	v_cvt_pk_bf16_f32 v33, v34, v35
	v_cvt_pk_bf16_f32 v34, v36, v37
	v_cvt_pk_bf16_f32 v35, v38, v39
	s_nop 0
	v_permlane32_swap_b32_e32 v32, v34
	v_permlane32_swap_b32_e32 v33, v35
	global_store_dwordx4 v[56:57], v[32:35], off offset:32
	global_load_dwordx4 v[32:35], v97, s[18:19] offset:128
	s_nop 0
	global_load_dwordx4 v[36:39], v97, s[18:19] offset:160
	v_lshlrev_b32_e32 v40, 16, v156
	v_and_b32_e32 v41, 0xffff0000, v156
	v_lshlrev_b32_e32 v42, 16, v157
	v_and_b32_e32 v43, 0xffff0000, v157
	v_lshlrev_b32_e32 v44, 16, v154
	v_and_b32_e32 v45, 0xffff0000, v154
	v_lshlrev_b32_e32 v46, 16, v155
	v_and_b32_e32 v47, 0xffff0000, v155
	s_waitcnt vmcnt(1)
	v_mul_f32_e32 v16, v16, v32
	v_mul_f32_e32 v17, v17, v33
	v_mul_f32_e32 v18, v18, v34
	v_mul_f32_e32 v19, v19, v35
	s_waitcnt vmcnt(0)
	v_mul_f32_e32 v20, v20, v36
	v_mul_f32_e32 v21, v21, v37
	v_mul_f32_e32 v22, v22, v38
	v_mul_f32_e32 v23, v23, v39
	v_mul_f32_e32 v16, v16, v40
	v_mul_f32_e32 v17, v17, v41
	v_mul_f32_e32 v18, v18, v42
	v_mul_f32_e32 v19, v19, v43
	v_mul_f32_e32 v20, v20, v44
	v_mul_f32_e32 v21, v21, v45
	v_mul_f32_e32 v22, v22, v46
	v_mul_f32_e32 v23, v23, v47
	v_cvt_pk_bf16_f32 v16, v16, v17
	v_cvt_pk_bf16_f32 v17, v18, v19
	v_cvt_pk_bf16_f32 v18, v20, v21
	v_cvt_pk_bf16_f32 v19, v22, v23
	s_nop 0
	v_permlane32_swap_b32_e32 v16, v18
	v_permlane32_swap_b32_e32 v17, v19
	global_store_dwordx4 v[56:57], v[16:19], off offset:64
	global_load_dwordx4 v[16:19], v97, s[18:19] offset:192
	s_nop 0
	global_load_dwordx4 v[20:23], v97, s[18:19] offset:224
	v_lshlrev_b32_e32 v32, 16, v152
	v_and_b32_e32 v33, 0xffff0000, v152
	v_lshlrev_b32_e32 v34, 16, v153
	v_and_b32_e32 v35, 0xffff0000, v153
	v_lshlrev_b32_e32 v36, 16, v150
	v_and_b32_e32 v37, 0xffff0000, v150
	v_lshlrev_b32_e32 v38, 16, v151
	v_and_b32_e32 v39, 0xffff0000, v151
	s_waitcnt vmcnt(1)
	v_mul_f32_e32 v16, v24, v16
	v_mul_f32_e32 v17, v25, v17
	v_mul_f32_e32 v18, v26, v18
	v_mul_f32_e32 v19, v27, v19
	s_waitcnt vmcnt(0)
	v_mul_f32_e32 v20, v28, v20
	v_mul_f32_e32 v21, v29, v21
	v_mul_f32_e32 v22, v30, v22
	v_mul_f32_e32 v23, v31, v23
	v_mul_f32_e32 v16, v16, v32
	v_mul_f32_e32 v17, v17, v33
	v_mul_f32_e32 v18, v18, v34
	v_mul_f32_e32 v19, v19, v35
	v_mul_f32_e32 v20, v20, v36
	v_mul_f32_e32 v21, v21, v37
	v_mul_f32_e32 v22, v22, v38
	v_mul_f32_e32 v23, v23, v39
	v_cvt_pk_bf16_f32 v16, v16, v17
	v_cvt_pk_bf16_f32 v17, v18, v19
	v_cvt_pk_bf16_f32 v18, v20, v21
	v_cvt_pk_bf16_f32 v19, v22, v23
	s_nop 0
	v_permlane32_swap_b32_e32 v16, v18
	v_permlane32_swap_b32_e32 v17, v19
	global_store_dwordx4 v[56:57], v[16:19], off offset:96
	s_barrier
	s_cbranch_vccz .LBB0_725

.LBB0_711:
	s_or_b64 exec, exec, s[4:5]
	ds_read_b32 v40, v40 offset:9984
	v_add_f32_e32 v37, v38, v37
	v_exp_f32_e64 v46, -v37
	v_and_b32_e32 v38, 0xffff0000, v175
	v_and_b32_e32 v123, 0xffff0000, v186
	s_waitcnt lgkmcnt(0)
	v_add_f32_e32 v40, v41, v40
	v_cndmask_b32_e32 v93, v40, v41, vcc
	v_and_b32_e32 v40, 0xfffff3f, v33
	v_mul_lo_u32 v142, v40, s39
	v_exp_f32_e32 v40, v37
	v_add_f32_e32 v37, v39, v37
	v_exp_f32_e32 v41, v37
	v_exp_f32_e64 v47, -v37
	v_and_b32_e32 v39, 0xffff0000, v176
	v_add_f32_e32 v37, v42, v37
	v_mul_f32_e32 v94, v40, v38
	v_mul_f32_e32 v95, v41, v39
	v_lshlrev_b32_e32 v41, 16, v176
	v_lshlrev_b32_e32 v40, 16, v175
	v_mul_f32_e32 v96, v46, v40
	v_mul_f32_e32 v97, v47, v41
	v_exp_f32_e32 v46, v37
	v_exp_f32_e64 v98, -v37
	v_add_f32_e32 v37, v43, v37
	v_exp_f32_e32 v47, v37
	v_exp_f32_e64 v99, -v37
	v_add_f32_e32 v37, v56, v37
	v_exp_f32_e32 v56, v37
	v_exp_f32_e64 v102, -v37
	v_add_f32_e32 v37, v57, v37
	v_exp_f32_e32 v57, v37
	v_exp_f32_e64 v103, -v37
	v_add_f32_e32 v37, v54, v37
	v_exp_f32_e32 v54, v37
	v_exp_f32_e64 v108, -v37
	v_add_f32_e32 v37, v55, v37
	v_exp_f32_e32 v55, v37
	v_exp_f32_e64 v109, -v37
	v_add_f32_e32 v37, v52, v37
	v_exp_f32_e32 v52, v37
	v_exp_f32_e64 v114, -v37
	v_add_f32_e32 v37, v53, v37
	v_exp_f32_e32 v53, v37
	v_exp_f32_e64 v115, -v37
	v_add_f32_e32 v37, v50, v37
	v_exp_f32_e32 v50, v37
	v_exp_f32_e64 v120, -v37
	v_add_f32_e32 v37, v51, v37
	v_exp_f32_e32 v51, v37
	v_and_b32_e32 v122, 0xffff0000, v185
	v_exp_f32_e64 v121, -v37
	v_add_f32_e32 v37, v48, v37
	v_mul_f32_e32 v124, v50, v122
	v_mul_f32_e32 v125, v51, v123
	v_exp_f32_e32 v48, v37
	v_exp_f32_e64 v50, -v37
	v_add_f32_e32 v37, v49, v37
	v_exp_f32_e32 v49, v37
	v_and_b32_e32 v129, 0xffff0000, v188
	v_and_b32_e32 v128, 0xffff0000, v187
	v_exp_f32_e64 v51, -v37
	v_add_f32_e32 v37, v44, v37
	v_mul_f32_e32 v130, v48, v128
	v_mul_f32_e32 v131, v49, v129
	v_exp_f32_e32 v44, v37
	v_exp_f32_e64 v48, -v37
	v_add_f32_e32 v37, v45, v37
	v_exp_f32_e32 v45, v37
	v_exp_f32_e64 v49, -v37
	v_and_b32_e32 v43, 0xffff0000, v178
	v_and_b32_e32 v42, 0xffff0000, v177
	v_and_b32_e32 v105, 0xffff0000, v180
	v_and_b32_e32 v104, 0xffff0000, v179
	v_and_b32_e32 v111, 0xffff0000, v182
	v_and_b32_e32 v110, 0xffff0000, v181
	v_lshlrev_b32_e32 v35, 5, v35
	v_mul_f32_e32 v100, v46, v42
	v_mul_f32_e32 v101, v47, v43
	v_mul_f32_e32 v56, v56, v104
	v_mul_f32_e32 v57, v57, v105
	v_mul_f32_e32 v54, v54, v110
	v_mul_f32_e32 v55, v55, v111
	v_and_b32_e32 v117, 0xffff0000, v184
	v_and_b32_e32 v116, 0xffff0000, v183
	v_lshlrev_b32_e32 v133, 16, v188
	v_lshlrev_b32_e32 v132, 16, v187
	v_and_b32_e32 v137, 0xffff0000, v190
	v_and_b32_e32 v136, 0xffff0000, v189
	v_lshlrev_b32_e32 v139, 16, v190
	v_lshlrev_b32_e32 v138, 16, v189
	v_lshlrev_b32_e32 v47, 16, v178
	v_lshlrev_b32_e32 v46, 16, v177
	v_lshlrev_b32_e32 v107, 16, v180
	v_lshlrev_b32_e32 v106, 16, v179
	v_lshlrev_b32_e32 v113, 16, v182
	v_lshlrev_b32_e32 v112, 16, v181
	v_mul_f32_e32 v52, v52, v116
	v_mul_f32_e32 v53, v53, v117
	v_mul_f32_e32 v134, v50, v132
	v_mul_f32_e32 v135, v51, v133
	v_mul_f32_e32 v44, v44, v136
	v_mul_f32_e32 v45, v45, v137
	v_mul_f32_e32 v140, v48, v138
	v_mul_f32_e32 v141, v49, v139
	v_add3_u32 v35, 0, v142, v35
	v_cvt_pk_bf16_f32 v48, v94, v95
	v_cvt_pk_bf16_f32 v49, v100, v101
	v_cvt_pk_bf16_f32 v50, v56, v57
	v_cvt_pk_bf16_f32 v51, v54, v55
	v_mul_f32_e32 v98, v98, v46
	v_mul_f32_e32 v99, v99, v47
	v_mul_f32_e32 v102, v102, v106
	v_mul_f32_e32 v103, v103, v107
	v_mul_f32_e32 v108, v108, v112
	v_mul_f32_e32 v109, v109, v113
	v_lshlrev_b32_e32 v119, 16, v184
	v_lshlrev_b32_e32 v118, 16, v183
	v_lshlrev_b32_e32 v127, 16, v186
	v_lshlrev_b32_e32 v126, 16, v185
	ds_write_b128 v35, v[48:51] offset:47104
	v_cvt_pk_bf16_f32 v48, v52, v53
	v_cvt_pk_bf16_f32 v49, v124, v125
	v_cvt_pk_bf16_f32 v50, v130, v131
	v_cvt_pk_bf16_f32 v51, v44, v45
	v_mul_f32_e32 v114, v114, v118
	v_mul_f32_e32 v115, v115, v119
	v_mul_f32_e32 v120, v120, v126
	v_mul_f32_e32 v121, v121, v127
	ds_write_b128 v35, v[48:51] offset:47120
	v_cvt_pk_bf16_f32 v48, v96, v97
	v_cvt_pk_bf16_f32 v49, v98, v99
	v_cvt_pk_bf16_f32 v50, v102, v103
	v_cvt_pk_bf16_f32 v51, v108, v109
	ds_write_b128 v35, v[48:51] offset:56320
	v_cvt_pk_bf16_f32 v48, v114, v115
	v_cvt_pk_bf16_f32 v49, v120, v121
	v_cvt_pk_bf16_f32 v50, v134, v135
	v_cvt_pk_bf16_f32 v51, v140, v141
	v_add_u32_e32 v37, 0xb800, v35
	ds_write_b128 v35, v[48:51] offset:56336
	v_add_f32_e32 v35, v31, v93
	v_exp_f32_e32 v31, v35
	v_exp_f32_e64 v45, -v35
	v_add_f32_e32 v35, v30, v35
	v_exp_f32_e32 v30, v35
	v_exp_f32_e64 v44, -v35
	v_add_f32_e32 v35, v29, v35
	v_exp_f32_e32 v29, v35
	v_exp_f32_e64 v49, -v35
	v_add_f32_e32 v35, v28, v35
	v_exp_f32_e32 v28, v35
	v_exp_f32_e64 v48, -v35
	v_add_f32_e32 v35, v27, v35
	v_exp_f32_e32 v27, v35
	v_exp_f32_e64 v51, -v35
	v_add_f32_e32 v35, v26, v35
	v_exp_f32_e32 v26, v35
	v_exp_f32_e64 v50, -v35
	v_add_f32_e32 v35, v25, v35
	v_exp_f32_e32 v25, v35
	v_exp_f32_e64 v53, -v35
	v_add_f32_e32 v35, v24, v35
	v_exp_f32_e32 v24, v35
	v_exp_f32_e64 v52, -v35
	v_add_f32_e32 v35, v23, v35
	v_exp_f32_e32 v23, v35
	v_exp_f32_e64 v55, -v35
	v_add_f32_e32 v35, v22, v35
	v_exp_f32_e32 v22, v35
	v_exp_f32_e64 v54, -v35
	v_add_f32_e32 v35, v21, v35
	v_exp_f32_e32 v21, v35
	v_exp_f32_e64 v57, -v35
	v_add_f32_e32 v35, v20, v35
	v_exp_f32_e32 v20, v35
	v_exp_f32_e64 v56, -v35
	v_add_f32_e32 v35, v19, v35
	v_exp_f32_e32 v19, v35
	v_exp_f32_e64 v95, -v35
	v_add_f32_e32 v35, v18, v35
	v_exp_f32_e32 v18, v35
	v_exp_f32_e64 v94, -v35
	v_add_f32_e32 v35, v17, v35
	v_exp_f32_e32 v17, v35
	v_exp_f32_e64 v97, -v35
	v_add_f32_e32 v35, v16, v35
	v_exp_f32_e32 v16, v35
	v_exp_f32_e64 v96, -v35
	s_add_i32 s42, s28, s31
	v_mul_f32_e32 v22, v22, v110
	v_mul_f32_e32 v23, v23, v111
	v_mul_f32_e32 v20, v20, v104
	v_mul_f32_e32 v21, v21, v105
	v_mul_f32_e32 v18, v18, v42
	v_mul_f32_e32 v19, v19, v43
	v_mul_f32_e32 v16, v16, v38
	v_mul_f32_e32 v17, v17, v39
	s_cmpk_gt_i32 s42, 0x5ff
	v_mul_f32_e32 v30, v30, v136
	v_mul_f32_e32 v31, v31, v137
	v_mul_f32_e32 v28, v28, v128
	v_mul_f32_e32 v29, v29, v129
	v_mul_f32_e32 v26, v26, v122
	v_mul_f32_e32 v27, v27, v123
	v_mul_f32_e32 v24, v24, v116
	v_mul_f32_e32 v25, v25, v117
	v_cvt_pk_bf16_f32 v16, v16, v17
	v_cvt_pk_bf16_f32 v17, v18, v19
	v_cvt_pk_bf16_f32 v18, v20, v21
	v_cvt_pk_bf16_f32 v19, v22, v23
	s_cselect_b64 s[26:27], -1, 0
	s_cmpk_lt_i32 s42, 0x600
	v_mul_f32_e32 v54, v54, v112
	v_mul_f32_e32 v55, v55, v113
	v_mul_f32_e32 v56, v56, v106
	v_mul_f32_e32 v57, v57, v107
	v_mul_f32_e32 v42, v94, v46
	v_mul_f32_e32 v43, v95, v47
	v_mul_f32_e32 v38, v96, v40
	v_mul_f32_e32 v39, v97, v41
	ds_write_b128 v37, v[16:19] offset:18432
	v_cvt_pk_bf16_f32 v16, v24, v25
	v_cvt_pk_bf16_f32 v17, v26, v27
	v_cvt_pk_bf16_f32 v18, v28, v29
	v_cvt_pk_bf16_f32 v19, v30, v31
	s_cselect_b32 s4, s42, -1
	v_mul_f32_e32 v44, v44, v138
	v_mul_f32_e32 v45, v45, v139
	v_mul_f32_e32 v48, v48, v132
	v_mul_f32_e32 v49, v49, v133
	v_mul_f32_e32 v50, v50, v126
	v_mul_f32_e32 v51, v51, v127
	v_mul_f32_e32 v52, v52, v118
	v_mul_f32_e32 v53, v53, v119
	ds_write_b128 v37, v[16:19] offset:18448
	v_cvt_pk_bf16_f32 v16, v38, v39
	v_cvt_pk_bf16_f32 v17, v42, v43
	v_cvt_pk_bf16_f32 v18, v56, v57
	v_cvt_pk_bf16_f32 v19, v54, v55
	v_lshrrev_b32_e32 v92, 2, v33
	ds_write_b128 v37, v[16:19] offset:27648
	v_cvt_pk_bf16_f32 v16, v52, v53
	v_cvt_pk_bf16_f32 v17, v50, v51
	v_cvt_pk_bf16_f32 v18, v48, v49
	v_cvt_pk_bf16_f32 v19, v44, v45
	s_cmp_lt_i32 s4, 0
	ds_write_b128 v37, v[16:19] offset:27664
	s_waitcnt lgkmcnt(0)
	s_barrier
	s_cbranch_scc1 .LBB0_713
	v_ashrrev_i32_e32 v16, 2, v33
	s_and_b32 s5, s4, 1
	s_lshl_b32 s4, s4, 5
	v_and_b32_e32 v16, 0xffffffc0, v16
	s_and_b32 s29, s4, 0x7fffffc0
	v_lshl_add_u32 v16, s5, 7, v16
	v_or_b32_e32 v16, v16, v197
	v_and_or_b32 v148, v92, 48, s29
	v_lshlrev_b64 v[18:19], 9, v[148:149]
	v_ashrrev_i32_e32 v17, 31, v16
	v_lshl_add_u64 v[20:21], s[12:13], 0, v[18:19]
	v_lshlrev_b64 v[16:17], 1, v[16:17]
	v_lshl_add_u64 v[20:21], v[20:21], 0, v[16:17]
	v_lshl_add_u64 v[18:19], s[10:11], 0, v[18:19]
	v_lshl_add_u64 v[16:17], v[18:19], 0, v[16:17]
	v_add_co_u32_e32 v18, vcc, s30, v20
	global_load_ushort v22, v[20:21], off
	global_load_ushort v23, v[20:21], off offset:512
	global_load_ushort v24, v[20:21], off offset:1024
	global_load_ushort v25, v[20:21], off offset:1536
	global_load_ushort v26, v[20:21], off offset:2048
	global_load_ushort v27, v[20:21], off offset:2560
	global_load_ushort v28, v[20:21], off offset:3072
	global_load_ushort v29, v[20:21], off offset:3584
	global_load_ushort v30, v[16:17], off
	global_load_ushort v31, v[16:17], off offset:512
	global_load_ushort v38, v[16:17], off offset:1024
	global_load_ushort v39, v[16:17], off offset:1536
	global_load_ushort v40, v[16:17], off offset:2048
	global_load_ushort v41, v[16:17], off offset:2560
	global_load_ushort v42, v[16:17], off offset:3072
	global_load_ushort v43, v[16:17], off offset:3584
	v_addc_co_u32_e32 v19, vcc, 0, v21, vcc
	v_add_co_u32_e32 v16, vcc, s30, v16
	s_lshl_b32 s4, s5, 9
	s_nop 0
	v_addc_co_u32_e32 v17, vcc, 0, v17, vcc
	global_load_ushort v44, v[18:19], off
	global_load_ushort v45, v[18:19], off offset:512
	global_load_ushort v46, v[18:19], off offset:1024
	global_load_ushort v47, v[18:19], off offset:1536
	global_load_ushort v48, v[18:19], off offset:2048
	global_load_ushort v49, v[18:19], off offset:2560
	global_load_ushort v50, v[18:19], off offset:3072
	global_load_ushort v51, v[18:19], off offset:3584
	global_load_ushort v52, v[16:17], off
	global_load_ushort v53, v[16:17], off offset:512
	global_load_ushort v54, v[16:17], off offset:1024
	global_load_ushort v55, v[16:17], off offset:1536
	global_load_ushort v56, v[16:17], off offset:2048
	global_load_ushort v57, v[16:17], off offset:2560
	global_load_ushort v93, v[16:17], off offset:3072
	global_load_ushort v94, v[16:17], off offset:3584
	v_ashrrev_i32_e32 v16, 3, v33
	v_add_u32_e32 v16, s29, v16
	v_ashrrev_i32_e32 v17, 31, v16
	v_lshlrev_b64 v[16:17], 7, v[16:17]
	s_add_u32 s4, s33, s4
	v_add_u32_e32 v20, s29, v62
	v_lshl_add_u64 v[16:17], s[14:15], 0, v[16:17]
	v_mov_b32_e32 v37, v149
	s_addc_u32 s5, s34, 0
	v_mov_b32_e32 v35, v149
	v_ashrrev_i32_e32 v21, 31, v20
	v_lshl_add_u64 v[16:17], v[16:17], 0, v[36:37]
	v_lshl_add_u64 v[18:19], s[4:5], 0, v[34:35]
	v_lshlrev_b64 v[20:21], 10, v[20:21]
	v_lshl_add_u64 v[20:21], v[18:19], 0, v[20:21]
	global_load_dwordx4 v[72:75], v[16:17], off
	global_load_dwordx4 v[76:79], v[20:21], off
	v_add_u32_e32 v16, s29, v61
	v_ashrrev_i32_e32 v17, 31, v16
	v_add_u32_e32 v20, s29, v60
	v_lshlrev_b64 v[16:17], 10, v[16:17]
	v_ashrrev_i32_e32 v21, 31, v20
	v_lshl_add_u64 v[16:17], v[18:19], 0, v[16:17]
	v_lshlrev_b64 v[20:21], 10, v[20:21]
	v_lshl_add_u64 v[20:21], v[18:19], 0, v[20:21]
	global_load_dwordx4 v[80:83], v[16:17], off
	global_load_dwordx4 v[84:87], v[20:21], off
	v_add_u32_e32 v16, s29, v59
	v_ashrrev_i32_e32 v17, 31, v16
	v_lshlrev_b64 v[16:17], 10, v[16:17]
	v_lshl_add_u64 v[16:17], v[18:19], 0, v[16:17]
	global_load_dwordx4 v[88:91], v[16:17], off
	s_waitcnt vmcnt(28)
	v_perm_b32 v175, v30, v22, s35
	s_waitcnt vmcnt(27)
	v_perm_b32 v176, v31, v23, s35
	s_waitcnt vmcnt(26)
	v_perm_b32 v177, v38, v24, s35
	s_waitcnt vmcnt(25)
	v_perm_b32 v178, v39, v25, s35
	s_waitcnt vmcnt(24)
	v_perm_b32 v179, v40, v26, s35
	s_waitcnt vmcnt(23)
	v_perm_b32 v180, v41, v27, s35
	s_waitcnt vmcnt(22)
	v_perm_b32 v181, v42, v28, s35
	s_waitcnt vmcnt(21)
	v_perm_b32 v182, v43, v29, s35
	s_waitcnt vmcnt(12)
	v_perm_b32 v183, v52, v44, s35
	s_waitcnt vmcnt(11)
	v_perm_b32 v184, v53, v45, s35
	s_waitcnt vmcnt(10)
	v_perm_b32 v185, v54, v46, s35
	s_waitcnt vmcnt(9)
	v_perm_b32 v186, v55, v47, s35
	s_waitcnt vmcnt(8)
	v_perm_b32 v187, v56, v48, s35
	s_waitcnt vmcnt(7)
	v_perm_b32 v188, v57, v49, s35
	s_waitcnt vmcnt(6)
	v_perm_b32 v189, v93, v50, s35
	s_waitcnt vmcnt(5)
	v_perm_b32 v190, v94, v51, s35
